# P4 epilogue guard flag prefetched in the K-loop (trip 26, column tile < 8) into v243; fast path no longer loads + waits vmcnt(0)
# baseline (speedup 1.0000x reference)
;     __device__ __forceinline__ void operator()(const f32x4 (&acc)[2][2][4][2], const Unit& u, int wr, int wc, int fr, int fq) const {
;     ...
;         if (need && u.pn < 8) { unsigned sp = 0u; while (__hip_atomic_load(guard, __ATOMIC_RELAXED, __HIP_MEMORY_SCOPE_AGENT) < need && ++sp < (1u << 22)) __builtin_amdgcn_s_sleep(2); }
.LBB0_808:
	ds_read_b128 v[144:147], v152
	ds_read_b128 v[156:159], v152 offset:1024
	ds_read_b128 v[160:163], v152 offset:2048
	ds_read_b128 v[164:167], v152 offset:3072
	ds_read_b128 v[168:171], v153
	ds_read_b128 v[172:175], v153 offset:1024
	ds_read_b128 v[176:179], v153 offset:2048
	ds_read_b128 v[180:183], v153 offset:3072
	s_add_u32 s34, s30, 0xfff80080
	s_addc_u32 s35, s31, -1
	s_cmp_eq_u32 s55, 28
	s_cselect_b32 s37, s19, s35
	s_cselect_b32 s36, s51, s34
	s_cselect_b32 s35, s17, s54
	s_cselect_b32 s34, s52, s53
	s_add_i32 m0, s27, 0xc000
	ds_read_b128 v[184:187], v154
	ds_read_b128 v[188:191], v154 offset:1024
	ds_read_b128 v[196:199], v154 offset:2048
	ds_read_b128 v[200:203], v154 offset:3072
	ds_read_b128 v[204:207], v154 offset:4096
	ds_read_b128 v[208:211], v154 offset:5120
	ds_read_b128 v[212:215], v154 offset:6144
	ds_read_b128 v[216:219], v154 offset:7168
	global_load_lds_dwordx4 v138, s[30:31]
	s_add_i32 m0, s27, 0xe000
	s_nop 0
	global_load_lds_dwordx4 v140, s[30:31]
	s_waitcnt vmcnt(8) lgkmcnt(0)
	s_barrier
	s_cmp_eq_u32 s55, 26
	s_cbranch_scc0 .Lp4g_skip
	s_cmp_lt_i32 s28, 8
	s_cbranch_scc0 .Lp4g_skip
	global_load_dword v243, v133, s[4:5] sc1
.Lp4g_skip:
	v_mfma_f32_16x16x32_bf16 v[126:129], v[144:147], v[184:187], v[126:129]
	v_mfma_f32_16x16x32_bf16 v[122:125], v[160:163], v[184:187], v[122:125]
	v_mfma_f32_16x16x32_bf16 v[110:113], v[144:147], v[196:199], v[110:113]
	v_mfma_f32_16x16x32_bf16 v[106:109], v[160:163], v[196:199], v[106:109]
	v_mfma_f32_16x16x32_bf16 v[94:97], v[144:147], v[204:207], v[94:97]
	v_mfma_f32_16x16x32_bf16 v[90:93], v[160:163], v[204:207], v[90:93]
	v_mfma_f32_16x16x32_bf16 v[78:81], v[144:147], v[212:215], v[78:81]
	v_mfma_f32_16x16x32_bf16 v[74:77], v[160:163], v[212:215], v[74:77]
	v_mfma_f32_16x16x32_bf16 v[126:129], v[156:159], v[188:191], v[126:129]
	v_mfma_f32_16x16x32_bf16 v[122:125], v[164:167], v[188:191], v[122:125]
	v_mfma_f32_16x16x32_bf16 v[110:113], v[156:159], v[200:203], v[110:113]
	v_mfma_f32_16x16x32_bf16 v[106:109], v[164:167], v[200:203], v[106:109]
	v_mfma_f32_16x16x32_bf16 v[94:97], v[156:159], v[208:211], v[94:97]
	v_mfma_f32_16x16x32_bf16 v[90:93], v[164:167], v[208:211], v[90:93]
	v_mfma_f32_16x16x32_bf16 v[78:81], v[156:159], v[216:219], v[78:81]
	v_mfma_f32_16x16x32_bf16 v[74:77], v[164:167], v[216:219], v[74:77]
	v_mfma_f32_16x16x32_bf16 v[118:121], v[168:171], v[184:187], v[118:121]
	v_mfma_f32_16x16x32_bf16 v[114:117], v[176:179], v[184:187], v[114:117]
	v_mfma_f32_16x16x32_bf16 v[102:105], v[168:171], v[196:199], v[102:105]
	v_mfma_f32_16x16x32_bf16 v[98:101], v[176:179], v[196:199], v[98:101]
	v_mfma_f32_16x16x32_bf16 v[86:89], v[168:171], v[204:207], v[86:89]
	v_mfma_f32_16x16x32_bf16 v[82:85], v[176:179], v[204:207], v[82:85]
	v_mfma_f32_16x16x32_bf16 v[70:73], v[168:171], v[212:215], v[70:73]
	v_mfma_f32_16x16x32_bf16 v[66:69], v[176:179], v[212:215], v[66:69]
	v_mfma_f32_16x16x32_bf16 v[118:121], v[172:175], v[188:191], v[118:121]
	v_mfma_f32_16x16x32_bf16 v[114:117], v[180:183], v[188:191], v[114:117]
	v_mfma_f32_16x16x32_bf16 v[102:105], v[172:175], v[200:203], v[102:105]
	v_mfma_f32_16x16x32_bf16 v[98:101], v[180:183], v[200:203], v[98:101]
	v_mfma_f32_16x16x32_bf16 v[86:89], v[172:175], v[208:211], v[86:89]
	v_mfma_f32_16x16x32_bf16 v[82:85], v[180:183], v[208:211], v[82:85]
	v_mfma_f32_16x16x32_bf16 v[70:73], v[172:175], v[216:219], v[70:73]
	v_mfma_f32_16x16x32_bf16 v[66:69], v[180:183], v[216:219], v[66:69]
	s_barrier
	s_add_i32 m0, s38, 0x10000
	ds_read_b128 v[184:187], v154 offset:16384
	ds_read_b128 v[188:191], v154 offset:17408
	ds_read_b128 v[196:199], v154 offset:18432
	ds_read_b128 v[200:203], v154 offset:19456
	ds_read_b128 v[204:207], v154 offset:20480
	ds_read_b128 v[208:211], v154 offset:21504
	ds_read_b128 v[212:215], v154 offset:22528
	ds_read_b128 v[216:219], v154 offset:23552
	global_load_lds_dwordx4 v132, s[34:35]
	s_add_i32 m0, s38, 0x12000
	s_add_u32 s56, s34, 0x80000
	s_addc_u32 s57, s35, 0
	global_load_lds_dwordx4 v136, s[34:35]
	s_add_i32 m0, s38, 0x14000
	s_nop 0
	global_load_lds_dwordx4 v132, s[56:57]
	s_add_i32 m0, s38, 0x16000
	s_nop 0
	global_load_lds_dwordx4 v136, s[56:57]
	s_mov_b32 m0, s27
	s_nop 0
	global_load_lds_dwordx4 v130, s[36:37]
	s_mov_b32 m0, s29
	s_nop 0
	global_load_lds_dwordx4 v134, s[36:37]
	s_waitcnt vmcnt(8) lgkmcnt(0)
	s_barrier
	v_mfma_f32_16x16x32_bf16 v[62:65], v[144:147], v[184:187], v[62:65]
	v_mfma_f32_16x16x32_bf16 v[58:61], v[160:163], v[184:187], v[58:61]
	v_mfma_f32_16x16x32_bf16 v[46:49], v[144:147], v[196:199], v[46:49]
	v_mfma_f32_16x16x32_bf16 v[42:45], v[160:163], v[196:199], v[42:45]
	v_mfma_f32_16x16x32_bf16 v[30:33], v[144:147], v[204:207], v[30:33]
	v_mfma_f32_16x16x32_bf16 v[26:29], v[160:163], v[204:207], v[26:29]
	v_mfma_f32_16x16x32_bf16 v[14:17], v[144:147], v[212:215], v[14:17]
	v_mfma_f32_16x16x32_bf16 v[10:13], v[160:163], v[212:215], v[10:13]
	v_mfma_f32_16x16x32_bf16 v[62:65], v[156:159], v[188:191], v[62:65]
	v_mfma_f32_16x16x32_bf16 v[58:61], v[164:167], v[188:191], v[58:61]
	v_mfma_f32_16x16x32_bf16 v[46:49], v[156:159], v[200:203], v[46:49]
	v_mfma_f32_16x16x32_bf16 v[42:45], v[164:167], v[200:203], v[42:45]
	v_mfma_f32_16x16x32_bf16 v[30:33], v[156:159], v[208:211], v[30:33]
	v_mfma_f32_16x16x32_bf16 v[26:29], v[164:167], v[208:211], v[26:29]
	v_mfma_f32_16x16x32_bf16 v[14:17], v[156:159], v[216:219], v[14:17]
	v_mfma_f32_16x16x32_bf16 v[10:13], v[164:167], v[216:219], v[10:13]
	v_mfma_f32_16x16x32_bf16 v[54:57], v[168:171], v[184:187], v[54:57]
	v_mfma_f32_16x16x32_bf16 v[50:53], v[176:179], v[184:187], v[50:53]
	v_mfma_f32_16x16x32_bf16 v[38:41], v[168:171], v[196:199], v[38:41]
	v_mfma_f32_16x16x32_bf16 v[34:37], v[176:179], v[196:199], v[34:37]
	v_mfma_f32_16x16x32_bf16 v[22:25], v[168:171], v[204:207], v[22:25]
	v_mfma_f32_16x16x32_bf16 v[18:21], v[176:179], v[204:207], v[18:21]
	v_mfma_f32_16x16x32_bf16 v[6:9], v[168:171], v[212:215], v[6:9]
	v_mfma_f32_16x16x32_bf16 v[2:5], v[176:179], v[212:215], v[2:5]
	v_mfma_f32_16x16x32_bf16 v[54:57], v[172:175], v[188:191], v[54:57]
	v_mfma_f32_16x16x32_bf16 v[50:53], v[180:183], v[188:191], v[50:53]
	v_mfma_f32_16x16x32_bf16 v[38:41], v[172:175], v[200:203], v[38:41]
	v_mfma_f32_16x16x32_bf16 v[34:37], v[180:183], v[200:203], v[34:37]
	v_mfma_f32_16x16x32_bf16 v[22:25], v[172:175], v[208:211], v[22:25]
	v_mfma_f32_16x16x32_bf16 v[18:21], v[180:183], v[208:211], v[18:21]
	v_mfma_f32_16x16x32_bf16 v[6:9], v[172:175], v[216:219], v[6:9]
	v_mfma_f32_16x16x32_bf16 v[2:5], v[180:183], v[216:219], v[2:5]
	s_barrier
;     __device__ __forceinline__ void operator()(const f32x4 (&acc)[2][2][4][2], const Unit& u, int wr, int wc, int fr, int fq) const {
;     ...
;         if (need && u.pn < 8) { unsigned sp = 0u; while (__hip_atomic_load(guard, __ATOMIC_RELAXED, __HIP_MEMORY_SCOPE_AGENT) < need && ++sp < (1u << 22)) __builtin_amdgcn_s_sleep(2); }
	ds_read_b128 v[144:147], v148
	ds_read_b128 v[156:159], v148 offset:1024
	ds_read_b128 v[160:163], v148 offset:2048
	ds_read_b128 v[164:167], v148 offset:3072
	ds_read_b128 v[168:171], v149
	ds_read_b128 v[172:175], v149 offset:1024
	ds_read_b128 v[176:179], v149 offset:2048
	ds_read_b128 v[180:183], v149 offset:3072
	s_add_u32 s36, s36, 0x80000
	s_addc_u32 s37, s37, 0
	s_mov_b32 m0, s39
	ds_read_b128 v[184:187], v154 offset:32768
	ds_read_b128 v[188:191], v154 offset:33792
	ds_read_b128 v[196:199], v154 offset:34816
	ds_read_b128 v[200:203], v154 offset:35840
	ds_read_b128 v[204:207], v154 offset:36864
	ds_read_b128 v[208:211], v154 offset:37888
	ds_read_b128 v[212:215], v154 offset:38912
	ds_read_b128 v[216:219], v154 offset:39936
	global_load_lds_dwordx4 v130, s[36:37]
	s_mov_b32 m0, s40
	s_nop 0
	global_load_lds_dwordx4 v134, s[36:37]
	s_waitcnt vmcnt(8) lgkmcnt(0)
	s_barrier
	v_mfma_f32_16x16x32_bf16 v[126:129], v[144:147], v[184:187], v[126:129]
	v_mfma_f32_16x16x32_bf16 v[122:125], v[160:163], v[184:187], v[122:125]
	v_mfma_f32_16x16x32_bf16 v[110:113], v[144:147], v[196:199], v[110:113]
	v_mfma_f32_16x16x32_bf16 v[106:109], v[160:163], v[196:199], v[106:109]
	v_mfma_f32_16x16x32_bf16 v[94:97], v[144:147], v[204:207], v[94:97]
	v_mfma_f32_16x16x32_bf16 v[90:93], v[160:163], v[204:207], v[90:93]
	v_mfma_f32_16x16x32_bf16 v[78:81], v[144:147], v[212:215], v[78:81]
	v_mfma_f32_16x16x32_bf16 v[74:77], v[160:163], v[212:215], v[74:77]
	v_mfma_f32_16x16x32_bf16 v[126:129], v[156:159], v[188:191], v[126:129]
	v_mfma_f32_16x16x32_bf16 v[122:125], v[164:167], v[188:191], v[122:125]
	v_mfma_f32_16x16x32_bf16 v[110:113], v[156:159], v[200:203], v[110:113]
	v_mfma_f32_16x16x32_bf16 v[106:109], v[164:167], v[200:203], v[106:109]
	v_mfma_f32_16x16x32_bf16 v[94:97], v[156:159], v[208:211], v[94:97]
	v_mfma_f32_16x16x32_bf16 v[90:93], v[164:167], v[208:211], v[90:93]
	v_mfma_f32_16x16x32_bf16 v[78:81], v[156:159], v[216:219], v[78:81]
	v_mfma_f32_16x16x32_bf16 v[74:77], v[164:167], v[216:219], v[74:77]
	v_mfma_f32_16x16x32_bf16 v[118:121], v[168:171], v[184:187], v[118:121]
	v_mfma_f32_16x16x32_bf16 v[114:117], v[176:179], v[184:187], v[114:117]
	v_mfma_f32_16x16x32_bf16 v[102:105], v[168:171], v[196:199], v[102:105]
	v_mfma_f32_16x16x32_bf16 v[98:101], v[176:179], v[196:199], v[98:101]
	v_mfma_f32_16x16x32_bf16 v[86:89], v[168:171], v[204:207], v[86:89]
	v_mfma_f32_16x16x32_bf16 v[82:85], v[176:179], v[204:207], v[82:85]
	v_mfma_f32_16x16x32_bf16 v[70:73], v[168:171], v[212:215], v[70:73]
	v_mfma_f32_16x16x32_bf16 v[66:69], v[176:179], v[212:215], v[66:69]
	v_mfma_f32_16x16x32_bf16 v[118:121], v[172:175], v[188:191], v[118:121]
	v_mfma_f32_16x16x32_bf16 v[114:117], v[180:183], v[188:191], v[114:117]
	v_mfma_f32_16x16x32_bf16 v[102:105], v[172:175], v[200:203], v[102:105]
	v_mfma_f32_16x16x32_bf16 v[98:101], v[180:183], v[200:203], v[98:101]
	v_mfma_f32_16x16x32_bf16 v[86:89], v[172:175], v[208:211], v[86:89]
	v_mfma_f32_16x16x32_bf16 v[82:85], v[180:183], v[208:211], v[82:85]
	v_mfma_f32_16x16x32_bf16 v[70:73], v[172:175], v[216:219], v[70:73]
	v_mfma_f32_16x16x32_bf16 v[66:69], v[180:183], v[216:219], v[66:69]
	s_barrier
	s_add_u32 s98, s36, 0xfff80080
	s_addc_u32 s99, s37, -1
	s_add_i32 m0, s38, 0x18000
	ds_read_b128 v[184:187], v154 offset:49152
	ds_read_b128 v[188:191], v154 offset:50176
	ds_read_b128 v[196:199], v154 offset:51200
	ds_read_b128 v[200:203], v154 offset:52224
	ds_read_b128 v[204:207], v154 offset:53248
	ds_read_b128 v[208:211], v154 offset:54272
	ds_read_b128 v[212:215], v154 offset:55296
	ds_read_b128 v[216:219], v154 offset:56320
	s_add_u32 s100, s34, 0x80
	s_addc_u32 s101, s35, 0
	global_load_lds_dwordx4 v132, s[100:101]
	s_add_i32 m0, s38, 0x1a000
	s_add_u32 s34, s34, 0x80080
	s_addc_u32 s35, s35, 0
	global_load_lds_dwordx4 v136, s[100:101]
	s_add_i32 m0, s38, 0x1c000
	s_nop 0
	global_load_lds_dwordx4 v132, s[34:35]
	s_add_i32 m0, s38, 0x1e000
	s_nop 0
	global_load_lds_dwordx4 v136, s[34:35]
	s_mov_b32 m0, s42
	s_nop 0
	global_load_lds_dwordx4 v130, s[98:99]
	s_mov_b32 m0, s43
	s_nop 0
	global_load_lds_dwordx4 v134, s[98:99]
	s_waitcnt vmcnt(8) lgkmcnt(0)
	s_barrier
	v_mfma_f32_16x16x32_bf16 v[62:65], v[144:147], v[184:187], v[62:65]
	v_mfma_f32_16x16x32_bf16 v[58:61], v[160:163], v[184:187], v[58:61]
	v_mfma_f32_16x16x32_bf16 v[46:49], v[144:147], v[196:199], v[46:49]
	v_mfma_f32_16x16x32_bf16 v[42:45], v[160:163], v[196:199], v[42:45]
	v_mfma_f32_16x16x32_bf16 v[30:33], v[144:147], v[204:207], v[30:33]
	v_mfma_f32_16x16x32_bf16 v[26:29], v[160:163], v[204:207], v[26:29]
	v_mfma_f32_16x16x32_bf16 v[14:17], v[144:147], v[212:215], v[14:17]
	v_mfma_f32_16x16x32_bf16 v[10:13], v[160:163], v[212:215], v[10:13]
	v_mfma_f32_16x16x32_bf16 v[62:65], v[156:159], v[188:191], v[62:65]
	v_mfma_f32_16x16x32_bf16 v[58:61], v[164:167], v[188:191], v[58:61]
	v_mfma_f32_16x16x32_bf16 v[46:49], v[156:159], v[200:203], v[46:49]
	v_mfma_f32_16x16x32_bf16 v[42:45], v[164:167], v[200:203], v[42:45]
	v_mfma_f32_16x16x32_bf16 v[30:33], v[156:159], v[208:211], v[30:33]
	v_mfma_f32_16x16x32_bf16 v[26:29], v[164:167], v[208:211], v[26:29]
	v_mfma_f32_16x16x32_bf16 v[14:17], v[156:159], v[216:219], v[14:17]
	v_mfma_f32_16x16x32_bf16 v[10:13], v[164:167], v[216:219], v[10:13]
	v_mfma_f32_16x16x32_bf16 v[54:57], v[168:171], v[184:187], v[54:57]
	v_mfma_f32_16x16x32_bf16 v[50:53], v[176:179], v[184:187], v[50:53]
	v_mfma_f32_16x16x32_bf16 v[38:41], v[168:171], v[196:199], v[38:41]
	v_mfma_f32_16x16x32_bf16 v[34:37], v[176:179], v[196:199], v[34:37]
	v_mfma_f32_16x16x32_bf16 v[22:25], v[168:171], v[204:207], v[22:25]
	v_mfma_f32_16x16x32_bf16 v[18:21], v[176:179], v[204:207], v[18:21]
	v_mfma_f32_16x16x32_bf16 v[6:9], v[168:171], v[212:215], v[6:9]
	v_mfma_f32_16x16x32_bf16 v[2:5], v[176:179], v[212:215], v[2:5]
	v_mfma_f32_16x16x32_bf16 v[54:57], v[172:175], v[188:191], v[54:57]
	v_mfma_f32_16x16x32_bf16 v[50:53], v[180:183], v[188:191], v[50:53]
	v_mfma_f32_16x16x32_bf16 v[38:41], v[172:175], v[200:203], v[38:41]
	v_mfma_f32_16x16x32_bf16 v[34:37], v[180:183], v[200:203], v[34:37]
	v_mfma_f32_16x16x32_bf16 v[22:25], v[172:175], v[208:211], v[22:25]
	v_mfma_f32_16x16x32_bf16 v[18:21], v[180:183], v[208:211], v[18:21]
	v_mfma_f32_16x16x32_bf16 v[6:9], v[172:175], v[216:219], v[6:9]
	v_mfma_f32_16x16x32_bf16 v[2:5], v[180:183], v[216:219], v[2:5]
	s_barrier
	s_add_i32 s55, s55, 2
	s_add_u32 s53, s53, 0x100
	s_addc_u32 s54, s54, 0
	s_add_u32 s30, s30, 0x100
	s_addc_u32 s31, s31, 0
	s_cmp_gt_u32 s55, 29
	s_cbranch_scc0 .LBB0_808
	s_and_b64 vcc, exec, s[12:13]
	s_cbranch_vccz .LBB0_811
	s_barrier
.LBB0_811:
	s_cmp_lt_i32 s28, 8
	s_cselect_b64 s[30:31], -1, 0
	s_and_b64 s[30:31], s[62:63], s[30:31]
	s_andn2_b64 vcc, exec, s[30:31]
	s_cbranch_vccnz .LBB0_823
	v_cmp_lt_u32_e32 vcc, s49, v243
	s_cbranch_vccnz .LBB0_823
	s_mov_b32 s17, 0x3ffff8
	s_branch .LBB0_815
